# inverted s_setprio in the four GEMM K-loops (load segment at prio 1, MFMA segment at prio 0)
# baseline (speedup 1.0000x reference)
.LBB0_289:
	ds_read_b128 v[148:151], v165
	ds_read_b128 v[152:155], v165 offset:1024
	ds_read_b128 v[156:159], v165 offset:2048
	ds_read_b128 v[168:171], v165 offset:3072
	ds_read_b128 v[172:175], v166
	ds_read_b128 v[176:179], v166 offset:1024
	ds_read_b128 v[180:183], v166 offset:2048
	ds_read_b128 v[184:187], v166 offset:3072
	s_add_u32 s54, s52, 0xfffc0080
	s_addc_u32 s55, s53, -1
	s_cmp_eq_u32 s85, 12
	s_cselect_b32 s57, s29, s55
	s_cselect_b32 s56, s81, s54
	s_cselect_b32 s55, s27, s84
	s_cselect_b32 s54, s82, s83
	v_lshl_add_u64 v[160:161], s[52:53], 0, v[140:141]
	s_add_i32 m0, s51, 0xc000
	ds_read_b128 v[188:191], v167
	ds_read_b128 v[192:195], v167 offset:1024
	ds_read_b128 v[200:203], v167 offset:2048
	ds_read_b128 v[204:207], v167 offset:3072
	ds_read_b128 v[208:211], v167 offset:4096
	ds_read_b128 v[212:215], v167 offset:5120
	ds_read_b128 v[216:219], v167 offset:6144
	ds_read_b128 v[220:223], v167 offset:7168
	global_load_lds_dwordx4 v[160:161], off
	v_lshl_add_u64 v[160:161], s[52:53], 0, v[142:143]
	s_add_i32 m0, s51, 0xe000
	s_nop 0
	global_load_lds_dwordx4 v[160:161], off
	s_waitcnt vmcnt(8)
	s_waitcnt lgkmcnt(0)
	s_barrier
	s_setprio 0
	s_waitcnt lgkmcnt(0)
	v_mfma_f32_16x16x32_bf16 v[126:129], v[148:151], v[188:191], v[126:129]
	v_mfma_f32_16x16x32_bf16 v[122:125], v[156:159], v[188:191], v[122:125]
	v_mfma_f32_16x16x32_bf16 v[110:113], v[148:151], v[200:203], v[110:113]
	v_mfma_f32_16x16x32_bf16 v[106:109], v[156:159], v[200:203], v[106:109]
	v_mfma_f32_16x16x32_bf16 v[94:97], v[148:151], v[208:211], v[94:97]
	v_mfma_f32_16x16x32_bf16 v[90:93], v[156:159], v[208:211], v[90:93]
	v_mfma_f32_16x16x32_bf16 v[78:81], v[148:151], v[216:219], v[78:81]
	v_mfma_f32_16x16x32_bf16 v[74:77], v[156:159], v[216:219], v[74:77]
	v_mfma_f32_16x16x32_bf16 v[126:129], v[152:155], v[192:195], v[126:129]
	v_mfma_f32_16x16x32_bf16 v[122:125], v[168:171], v[192:195], v[122:125]
	v_mfma_f32_16x16x32_bf16 v[110:113], v[152:155], v[204:207], v[110:113]
	v_mfma_f32_16x16x32_bf16 v[106:109], v[168:171], v[204:207], v[106:109]
	v_mfma_f32_16x16x32_bf16 v[94:97], v[152:155], v[212:215], v[94:97]
	v_mfma_f32_16x16x32_bf16 v[90:93], v[168:171], v[212:215], v[90:93]
	v_mfma_f32_16x16x32_bf16 v[78:81], v[152:155], v[220:223], v[78:81]
	v_mfma_f32_16x16x32_bf16 v[74:77], v[168:171], v[220:223], v[74:77]
	s_setprio 1
	s_setprio 0
	v_mfma_f32_16x16x32_bf16 v[118:121], v[172:175], v[188:191], v[118:121]
	v_mfma_f32_16x16x32_bf16 v[114:117], v[180:183], v[188:191], v[114:117]
	v_mfma_f32_16x16x32_bf16 v[102:105], v[172:175], v[200:203], v[102:105]
	v_mfma_f32_16x16x32_bf16 v[98:101], v[180:183], v[200:203], v[98:101]
	v_mfma_f32_16x16x32_bf16 v[86:89], v[172:175], v[208:211], v[86:89]
	v_mfma_f32_16x16x32_bf16 v[82:85], v[180:183], v[208:211], v[82:85]
	v_mfma_f32_16x16x32_bf16 v[70:73], v[172:175], v[216:219], v[70:73]
	v_mfma_f32_16x16x32_bf16 v[66:69], v[180:183], v[216:219], v[66:69]
	v_mfma_f32_16x16x32_bf16 v[118:121], v[176:179], v[192:195], v[118:121]
	v_mfma_f32_16x16x32_bf16 v[114:117], v[184:187], v[192:195], v[114:117]
	v_mfma_f32_16x16x32_bf16 v[102:105], v[176:179], v[204:207], v[102:105]
	v_mfma_f32_16x16x32_bf16 v[98:101], v[184:187], v[204:207], v[98:101]
	v_mfma_f32_16x16x32_bf16 v[86:89], v[176:179], v[212:215], v[86:89]
	v_mfma_f32_16x16x32_bf16 v[82:85], v[184:187], v[212:215], v[82:85]
	v_mfma_f32_16x16x32_bf16 v[70:73], v[176:179], v[220:223], v[70:73]
	v_mfma_f32_16x16x32_bf16 v[66:69], v[184:187], v[220:223], v[66:69]
	s_setprio 1
	s_barrier
	s_add_i32 s86, s74, s64
	v_lshl_add_u64 v[160:161], s[54:55], 0, v[132:133]
	s_mov_b32 m0, s86
	ds_read_b128 v[188:191], v167 offset:16384
	ds_read_b128 v[192:195], v167 offset:17408
	ds_read_b128 v[200:203], v167 offset:18432
	ds_read_b128 v[204:207], v167 offset:19456
	ds_read_b128 v[208:211], v167 offset:20480
	ds_read_b128 v[212:215], v167 offset:21504
	ds_read_b128 v[216:219], v167 offset:22528
	ds_read_b128 v[220:223], v167 offset:23552
	global_load_lds_dwordx4 v[160:161], off
	s_add_i32 m0, s86, 0x2000
	s_add_u32 s86, s54, 0x40000
	v_lshl_add_u64 v[196:197], s[54:55], 0, v[136:137]
	s_addc_u32 s87, s55, 0
	s_add_i32 s88, s75, s64
	global_load_lds_dwordx4 v[196:197], off
	v_lshl_add_u64 v[224:225], s[86:87], 0, v[132:133]
	s_mov_b32 m0, s88
	v_lshl_add_u64 v[226:227], s[56:57], 0, v[134:135]
	global_load_lds_dwordx4 v[224:225], off
	v_lshl_add_u64 v[224:225], s[86:87], 0, v[136:137]
	s_add_i32 m0, s88, 0x2000
	s_nop 0
	global_load_lds_dwordx4 v[224:225], off
	v_lshl_add_u64 v[224:225], s[56:57], 0, v[130:131]
	s_mov_b32 m0, s51
	s_nop 0
	global_load_lds_dwordx4 v[224:225], off
	s_mov_b32 m0, s65
	s_nop 0
	global_load_lds_dwordx4 v[226:227], off
	s_waitcnt vmcnt(8)
	s_waitcnt lgkmcnt(0)
	s_barrier
	s_setprio 0
	s_waitcnt lgkmcnt(0)
	v_mfma_f32_16x16x32_bf16 v[62:65], v[148:151], v[188:191], v[62:65]
	v_mfma_f32_16x16x32_bf16 v[58:61], v[156:159], v[188:191], v[58:61]
	v_mfma_f32_16x16x32_bf16 v[46:49], v[148:151], v[200:203], v[46:49]
	v_mfma_f32_16x16x32_bf16 v[42:45], v[156:159], v[200:203], v[42:45]
	v_mfma_f32_16x16x32_bf16 v[30:33], v[148:151], v[208:211], v[30:33]
	v_mfma_f32_16x16x32_bf16 v[26:29], v[156:159], v[208:211], v[26:29]
	v_mfma_f32_16x16x32_bf16 v[14:17], v[148:151], v[216:219], v[14:17]
	v_mfma_f32_16x16x32_bf16 v[10:13], v[156:159], v[216:219], v[10:13]
	v_mfma_f32_16x16x32_bf16 v[62:65], v[152:155], v[192:195], v[62:65]
	v_mfma_f32_16x16x32_bf16 v[58:61], v[168:171], v[192:195], v[58:61]
	v_mfma_f32_16x16x32_bf16 v[46:49], v[152:155], v[204:207], v[46:49]
	v_mfma_f32_16x16x32_bf16 v[42:45], v[168:171], v[204:207], v[42:45]
	v_mfma_f32_16x16x32_bf16 v[30:33], v[152:155], v[212:215], v[30:33]
	v_mfma_f32_16x16x32_bf16 v[26:29], v[168:171], v[212:215], v[26:29]
	v_mfma_f32_16x16x32_bf16 v[14:17], v[152:155], v[220:223], v[14:17]
	v_mfma_f32_16x16x32_bf16 v[10:13], v[168:171], v[220:223], v[10:13]
	s_setprio 1
	s_setprio 0
	v_mfma_f32_16x16x32_bf16 v[54:57], v[172:175], v[188:191], v[54:57]
	v_mfma_f32_16x16x32_bf16 v[50:53], v[180:183], v[188:191], v[50:53]
	v_mfma_f32_16x16x32_bf16 v[38:41], v[172:175], v[200:203], v[38:41]
	v_mfma_f32_16x16x32_bf16 v[34:37], v[180:183], v[200:203], v[34:37]
	v_mfma_f32_16x16x32_bf16 v[22:25], v[172:175], v[208:211], v[22:25]
	v_mfma_f32_16x16x32_bf16 v[18:21], v[180:183], v[208:211], v[18:21]
	v_mfma_f32_16x16x32_bf16 v[6:9], v[172:175], v[216:219], v[6:9]
	v_mfma_f32_16x16x32_bf16 v[2:5], v[180:183], v[216:219], v[2:5]
	v_mfma_f32_16x16x32_bf16 v[54:57], v[176:179], v[192:195], v[54:57]
	v_mfma_f32_16x16x32_bf16 v[50:53], v[184:187], v[192:195], v[50:53]
	v_mfma_f32_16x16x32_bf16 v[38:41], v[176:179], v[204:207], v[38:41]
	v_mfma_f32_16x16x32_bf16 v[34:37], v[184:187], v[204:207], v[34:37]
	v_mfma_f32_16x16x32_bf16 v[22:25], v[176:179], v[212:215], v[22:25]
	v_mfma_f32_16x16x32_bf16 v[18:21], v[184:187], v[212:215], v[18:21]
	v_mfma_f32_16x16x32_bf16 v[6:9], v[176:179], v[220:223], v[6:9]
	v_mfma_f32_16x16x32_bf16 v[2:5], v[184:187], v[220:223], v[2:5]
	s_setprio 1
	s_barrier
	s_add_i32 s86, 0, 0x18000
	v_add_u32_e32 v138, s86, v162
	s_add_i32 s87, 0, 0x1c000
	ds_read_b128 v[148:151], v138
	ds_read_b128 v[152:155], v138 offset:1024
	ds_read_b128 v[156:159], v138 offset:2048
	ds_read_b128 v[168:171], v138 offset:3072
	v_add_u32_e32 v138, s87, v162
	ds_read_b128 v[172:175], v138
	ds_read_b128 v[176:179], v138 offset:1024
	ds_read_b128 v[180:183], v138 offset:2048
	ds_read_b128 v[184:187], v138 offset:3072
	s_add_u32 s56, s56, 0x40000
	s_addc_u32 s57, s57, 0
	s_mov_b32 m0, s66
	v_lshl_add_u64 v[228:229], s[56:57], 0, v[130:131]
	ds_read_b128 v[188:191], v167 offset:32768
	ds_read_b128 v[192:195], v167 offset:33792
	ds_read_b128 v[200:203], v167 offset:34816
	ds_read_b128 v[204:207], v167 offset:35840
	ds_read_b128 v[208:211], v167 offset:36864
	ds_read_b128 v[212:215], v167 offset:37888
	ds_read_b128 v[216:219], v167 offset:38912
	ds_read_b128 v[220:223], v167 offset:39936
	global_load_lds_dwordx4 v[228:229], off
	v_lshl_add_u64 v[228:229], s[56:57], 0, v[134:135]
	s_mov_b32 m0, s67
	s_nop 0
	global_load_lds_dwordx4 v[228:229], off
	s_waitcnt vmcnt(8)
	s_waitcnt lgkmcnt(0)
	s_barrier
	s_setprio 0
	s_waitcnt lgkmcnt(0)
	v_mfma_f32_16x16x32_bf16 v[126:129], v[148:151], v[188:191], v[126:129]
	v_mfma_f32_16x16x32_bf16 v[122:125], v[156:159], v[188:191], v[122:125]
	v_mfma_f32_16x16x32_bf16 v[110:113], v[148:151], v[200:203], v[110:113]
	v_mfma_f32_16x16x32_bf16 v[106:109], v[156:159], v[200:203], v[106:109]
	v_mfma_f32_16x16x32_bf16 v[94:97], v[148:151], v[208:211], v[94:97]
	v_mfma_f32_16x16x32_bf16 v[90:93], v[156:159], v[208:211], v[90:93]
	v_mfma_f32_16x16x32_bf16 v[78:81], v[148:151], v[216:219], v[78:81]
	v_mfma_f32_16x16x32_bf16 v[74:77], v[156:159], v[216:219], v[74:77]
	v_mfma_f32_16x16x32_bf16 v[126:129], v[152:155], v[192:195], v[126:129]
	v_mfma_f32_16x16x32_bf16 v[122:125], v[168:171], v[192:195], v[122:125]
	v_mfma_f32_16x16x32_bf16 v[110:113], v[152:155], v[204:207], v[110:113]
	v_mfma_f32_16x16x32_bf16 v[106:109], v[168:171], v[204:207], v[106:109]
	v_mfma_f32_16x16x32_bf16 v[94:97], v[152:155], v[212:215], v[94:97]
	v_mfma_f32_16x16x32_bf16 v[90:93], v[168:171], v[212:215], v[90:93]
	v_mfma_f32_16x16x32_bf16 v[78:81], v[152:155], v[220:223], v[78:81]
	v_mfma_f32_16x16x32_bf16 v[74:77], v[168:171], v[220:223], v[74:77]
	s_setprio 1
	s_setprio 0
	v_mfma_f32_16x16x32_bf16 v[118:121], v[172:175], v[188:191], v[118:121]
	v_mfma_f32_16x16x32_bf16 v[114:117], v[180:183], v[188:191], v[114:117]
	v_mfma_f32_16x16x32_bf16 v[102:105], v[172:175], v[200:203], v[102:105]
	v_mfma_f32_16x16x32_bf16 v[98:101], v[180:183], v[200:203], v[98:101]
	v_mfma_f32_16x16x32_bf16 v[86:89], v[172:175], v[208:211], v[86:89]
	v_mfma_f32_16x16x32_bf16 v[82:85], v[180:183], v[208:211], v[82:85]
	v_mfma_f32_16x16x32_bf16 v[70:73], v[172:175], v[216:219], v[70:73]
	v_mfma_f32_16x16x32_bf16 v[66:69], v[180:183], v[216:219], v[66:69]
	v_mfma_f32_16x16x32_bf16 v[118:121], v[176:179], v[192:195], v[118:121]
	v_mfma_f32_16x16x32_bf16 v[114:117], v[184:187], v[192:195], v[114:117]
	v_mfma_f32_16x16x32_bf16 v[102:105], v[176:179], v[204:207], v[102:105]
	v_mfma_f32_16x16x32_bf16 v[98:101], v[184:187], v[204:207], v[98:101]
	v_mfma_f32_16x16x32_bf16 v[86:89], v[176:179], v[212:215], v[86:89]
	v_mfma_f32_16x16x32_bf16 v[82:85], v[184:187], v[212:215], v[82:85]
	v_mfma_f32_16x16x32_bf16 v[70:73], v[176:179], v[220:223], v[70:73]
	v_mfma_f32_16x16x32_bf16 v[66:69], v[184:187], v[220:223], v[66:69]
	s_setprio 1
	s_barrier
	s_add_i32 s56, s86, s64
	v_lshl_add_u64 v[160:161], v[160:161], 0, s[14:15]
	s_mov_b32 m0, s56
	ds_read_b128 v[188:191], v167 offset:49152
	ds_read_b128 v[192:195], v167 offset:50176
	ds_read_b128 v[200:203], v167 offset:51200
	ds_read_b128 v[204:207], v167 offset:52224
	ds_read_b128 v[208:211], v167 offset:53248
	ds_read_b128 v[212:215], v167 offset:54272
	ds_read_b128 v[216:219], v167 offset:55296
	ds_read_b128 v[220:223], v167 offset:56320
	global_load_lds_dwordx4 v[160:161], off
	s_add_i32 m0, s56, 0x2000
	s_add_u32 s54, s54, 0x40080
	v_lshl_add_u64 v[160:161], v[196:197], 0, s[14:15]
	s_addc_u32 s55, s55, 0
	s_add_i32 s56, s87, s64
	global_load_lds_dwordx4 v[160:161], off
	v_lshl_add_u64 v[160:161], s[54:55], 0, v[132:133]
	s_mov_b32 m0, s56
	s_nop 0
	global_load_lds_dwordx4 v[160:161], off
	v_lshl_add_u64 v[160:161], s[54:55], 0, v[136:137]
	s_add_i32 m0, s56, 0x2000
	s_nop 0
	global_load_lds_dwordx4 v[160:161], off
	v_lshl_add_u64 v[160:161], v[224:225], 0, s[14:15]
	s_mov_b32 m0, s68
	s_nop 0
	global_load_lds_dwordx4 v[160:161], off
	v_lshl_add_u64 v[160:161], v[226:227], 0, s[14:15]
	s_mov_b32 m0, s69
	s_nop 0
	global_load_lds_dwordx4 v[160:161], off
	s_waitcnt vmcnt(8)
	s_waitcnt lgkmcnt(0)
	s_barrier
	s_setprio 0
	s_waitcnt lgkmcnt(0)
	v_mfma_f32_16x16x32_bf16 v[62:65], v[148:151], v[188:191], v[62:65]
	v_mfma_f32_16x16x32_bf16 v[58:61], v[156:159], v[188:191], v[58:61]
	v_mfma_f32_16x16x32_bf16 v[46:49], v[148:151], v[200:203], v[46:49]
	v_mfma_f32_16x16x32_bf16 v[42:45], v[156:159], v[200:203], v[42:45]
	v_mfma_f32_16x16x32_bf16 v[30:33], v[148:151], v[208:211], v[30:33]
	v_mfma_f32_16x16x32_bf16 v[26:29], v[156:159], v[208:211], v[26:29]
	v_mfma_f32_16x16x32_bf16 v[14:17], v[148:151], v[216:219], v[14:17]
	v_mfma_f32_16x16x32_bf16 v[10:13], v[156:159], v[216:219], v[10:13]
	v_mfma_f32_16x16x32_bf16 v[62:65], v[152:155], v[192:195], v[62:65]
	v_mfma_f32_16x16x32_bf16 v[58:61], v[168:171], v[192:195], v[58:61]
	v_mfma_f32_16x16x32_bf16 v[46:49], v[152:155], v[204:207], v[46:49]
	v_mfma_f32_16x16x32_bf16 v[42:45], v[168:171], v[204:207], v[42:45]
	v_mfma_f32_16x16x32_bf16 v[30:33], v[152:155], v[212:215], v[30:33]
	v_mfma_f32_16x16x32_bf16 v[26:29], v[168:171], v[212:215], v[26:29]
	v_mfma_f32_16x16x32_bf16 v[14:17], v[152:155], v[220:223], v[14:17]
	v_mfma_f32_16x16x32_bf16 v[10:13], v[168:171], v[220:223], v[10:13]
	s_setprio 1
	s_setprio 0
	v_mfma_f32_16x16x32_bf16 v[54:57], v[172:175], v[188:191], v[54:57]
	v_mfma_f32_16x16x32_bf16 v[50:53], v[180:183], v[188:191], v[50:53]
	v_mfma_f32_16x16x32_bf16 v[38:41], v[172:175], v[200:203], v[38:41]
	v_mfma_f32_16x16x32_bf16 v[34:37], v[180:183], v[200:203], v[34:37]
	v_mfma_f32_16x16x32_bf16 v[22:25], v[172:175], v[208:211], v[22:25]
	v_mfma_f32_16x16x32_bf16 v[18:21], v[180:183], v[208:211], v[18:21]
	v_mfma_f32_16x16x32_bf16 v[6:9], v[172:175], v[216:219], v[6:9]
	v_mfma_f32_16x16x32_bf16 v[2:5], v[180:183], v[216:219], v[2:5]
	v_mfma_f32_16x16x32_bf16 v[54:57], v[176:179], v[192:195], v[54:57]
	v_mfma_f32_16x16x32_bf16 v[50:53], v[184:187], v[192:195], v[50:53]
	v_mfma_f32_16x16x32_bf16 v[38:41], v[176:179], v[204:207], v[38:41]
	v_mfma_f32_16x16x32_bf16 v[34:37], v[184:187], v[204:207], v[34:37]
	v_mfma_f32_16x16x32_bf16 v[22:25], v[176:179], v[212:215], v[22:25]
	v_mfma_f32_16x16x32_bf16 v[18:21], v[184:187], v[212:215], v[18:21]
	v_mfma_f32_16x16x32_bf16 v[6:9], v[176:179], v[220:223], v[6:9]
	v_mfma_f32_16x16x32_bf16 v[2:5], v[184:187], v[220:223], v[2:5]
	s_setprio 1
	s_barrier
	s_add_i32 s85, s85, 2
	s_add_u32 s52, s52, 0x100
	s_addc_u32 s53, s53, 0
	s_add_u32 s83, s83, 0x100
	s_addc_u32 s84, s84, 0
	s_cmp_gt_u32 s85, 13
	s_cbranch_scc0 .LBB0_289
	s_and_b64 vcc, exec, s[18:19]
	s_cbranch_vccz .LBB0_292
	s_barrier

.LBB0_328:
	s_setprio 0
	s_cmp_gt_i32 s35, 2
	s_cselect_b64 s[4:5], -1, 0
	s_and_b64 s[6:7], s[8:9], s[4:5]
	s_andn2_b64 vcc, exec, s[6:7]
	s_cbranch_vccnz .LBB0_377
	s_waitcnt vmcnt(0)
	v_cmp_eq_u32_e32 vcc, 0, v0
	s_waitcnt vmcnt(0) lgkmcnt(0)
	s_barrier
	s_and_saveexec_b64 s[6:7], vcc
	s_cbranch_execz .LBB0_376
	v_mov_b32_e32 v1, s33
	s_waitcnt vmcnt(0) expcnt(0) lgkmcnt(0)
	ds_read_b32 v3, v1
	ds_read_b32 v1, v1 offset:4
	s_waitcnt lgkmcnt(1)
	v_cmp_ne_u32_e32 vcc, 0, v3
	s_cbranch_vccnz .LBB0_345
	s_load_dwordx2 s[12:13], s[42:43], 0x4
	s_add_u32 s8, s38, 0x4200
	s_addc_u32 s9, s39, 0
	s_add_u32 s10, s38, 0x4400
	s_addc_u32 s11, s39, 0
	s_waitcnt lgkmcnt(0)
	s_mul_i32 s66, s12, s30
	s_add_u32 s12, s38, 0x4500
	s_mul_i32 s66, s66, s13
	s_addc_u32 s13, s39, 0
	s_add_u32 s14, s38, 0x4600
	s_addc_u32 s15, s39, 0
	s_add_u32 s18, s38, 0x4700
	s_addc_u32 s19, s39, 0
	s_add_u32 s20, s38, 0x4800
	s_addc_u32 s21, s39, 0
	s_add_u32 s22, s38, 0x4900
	s_addc_u32 s23, s39, 0
	s_add_u32 s24, s38, 0x4a00
	s_addc_u32 s25, s39, 0
	s_add_u32 s26, s38, 0x4b00
	s_addc_u32 s27, s39, 0
	s_add_u32 s28, s38, 0x4c00
	s_addc_u32 s29, s39, 0
	s_add_u32 s46, s38, 0x4d00
	s_addc_u32 s47, s39, 0
	s_add_u32 s48, s38, 0x4e00
	s_addc_u32 s49, s39, 0
	s_add_u32 s50, s38, 0x4f00
	s_addc_u32 s51, s39, 0
	s_add_u32 s52, s38, 0x5000
	s_addc_u32 s53, s39, 0
	s_add_u32 s54, s38, 0x5100
	s_addc_u32 s55, s39, 0
	s_add_u32 s56, s38, 0x5200
	s_addc_u32 s57, s39, 0
	s_add_u32 s58, s38, 0x5300
	s_addc_u32 s59, s39, 0
	s_mov_b32 s67, 1
	v_mov_b32_e32 v17, 0
	s_branch .LBB0_333

.LBB0_557:
	ds_read_b128 v[130:133], v190
	ds_read_b128 v[134:137], v190 offset:1024
	ds_read_b128 v[138:141], v190 offset:2048
	ds_read_b128 v[142:145], v190 offset:3072
	ds_read_b128 v[146:149], v191
	ds_read_b128 v[150:153], v191 offset:1024
	ds_read_b128 v[170:173], v191 offset:2048
	ds_read_b128 v[174:177], v191 offset:3072
	s_add_u32 s54, s52, 0xfffc0080
	s_addc_u32 s55, s53, -1
	s_cmp_eq_u32 s78, 12
	s_cselect_b32 s57, s47, s55
	s_cselect_b32 s56, s74, s54
	s_cselect_b32 s55, s29, s77
	s_cselect_b32 s54, s75, s76
	v_lshl_add_u64 v[186:187], s[52:53], 0, v[162:163]
	s_add_i32 m0, s11, 0xc000
	ds_read_b128 v[178:181], v192
	ds_read_b128 v[182:185], v192 offset:1024
	ds_read_b128 v[194:197], v192 offset:2048
	ds_read_b128 v[200:203], v192 offset:3072
	ds_read_b128 v[204:207], v192 offset:4096
	ds_read_b128 v[208:211], v192 offset:5120
	ds_read_b128 v[212:215], v192 offset:6144
	ds_read_b128 v[216:219], v192 offset:7168
	global_load_lds_dwordx4 v[186:187], off
	v_lshl_add_u64 v[186:187], s[52:53], 0, v[164:165]
	s_add_i32 m0, s11, 0xe000
	s_nop 0
	global_load_lds_dwordx4 v[186:187], off
	s_waitcnt vmcnt(8)
	s_waitcnt lgkmcnt(0)
	s_barrier
	s_setprio 0
	s_waitcnt lgkmcnt(0)
	v_mfma_f32_16x16x32_bf16 v[126:129], v[130:133], v[178:181], v[126:129]
	v_mfma_f32_16x16x32_bf16 v[122:125], v[138:141], v[178:181], v[122:125]
	v_mfma_f32_16x16x32_bf16 v[110:113], v[130:133], v[194:197], v[110:113]
	v_mfma_f32_16x16x32_bf16 v[106:109], v[138:141], v[194:197], v[106:109]
	v_mfma_f32_16x16x32_bf16 v[94:97], v[130:133], v[204:207], v[94:97]
	v_mfma_f32_16x16x32_bf16 v[90:93], v[138:141], v[204:207], v[90:93]
	v_mfma_f32_16x16x32_bf16 v[78:81], v[130:133], v[212:215], v[78:81]
	v_mfma_f32_16x16x32_bf16 v[74:77], v[138:141], v[212:215], v[74:77]
	v_mfma_f32_16x16x32_bf16 v[126:129], v[134:137], v[182:185], v[126:129]
	v_mfma_f32_16x16x32_bf16 v[122:125], v[142:145], v[182:185], v[122:125]
	v_mfma_f32_16x16x32_bf16 v[110:113], v[134:137], v[200:203], v[110:113]
	v_mfma_f32_16x16x32_bf16 v[106:109], v[142:145], v[200:203], v[106:109]
	v_mfma_f32_16x16x32_bf16 v[94:97], v[134:137], v[208:211], v[94:97]
	v_mfma_f32_16x16x32_bf16 v[90:93], v[142:145], v[208:211], v[90:93]
	v_mfma_f32_16x16x32_bf16 v[78:81], v[134:137], v[216:219], v[78:81]
	v_mfma_f32_16x16x32_bf16 v[74:77], v[142:145], v[216:219], v[74:77]
	s_setprio 1
	s_setprio 0
	v_mfma_f32_16x16x32_bf16 v[118:121], v[146:149], v[178:181], v[118:121]
	v_mfma_f32_16x16x32_bf16 v[114:117], v[170:173], v[178:181], v[114:117]
	v_mfma_f32_16x16x32_bf16 v[102:105], v[146:149], v[194:197], v[102:105]
	v_mfma_f32_16x16x32_bf16 v[98:101], v[170:173], v[194:197], v[98:101]
	v_mfma_f32_16x16x32_bf16 v[86:89], v[146:149], v[204:207], v[86:89]
	v_mfma_f32_16x16x32_bf16 v[82:85], v[170:173], v[204:207], v[82:85]
	v_mfma_f32_16x16x32_bf16 v[70:73], v[146:149], v[212:215], v[70:73]
	v_mfma_f32_16x16x32_bf16 v[66:69], v[170:173], v[212:215], v[66:69]
	v_mfma_f32_16x16x32_bf16 v[118:121], v[150:153], v[182:185], v[118:121]
	v_mfma_f32_16x16x32_bf16 v[114:117], v[174:177], v[182:185], v[114:117]
	v_mfma_f32_16x16x32_bf16 v[102:105], v[150:153], v[200:203], v[102:105]
	v_mfma_f32_16x16x32_bf16 v[98:101], v[174:177], v[200:203], v[98:101]
	v_mfma_f32_16x16x32_bf16 v[86:89], v[150:153], v[208:211], v[86:89]
	v_mfma_f32_16x16x32_bf16 v[82:85], v[174:177], v[208:211], v[82:85]
	v_mfma_f32_16x16x32_bf16 v[70:73], v[150:153], v[216:219], v[70:73]
	v_mfma_f32_16x16x32_bf16 v[66:69], v[174:177], v[216:219], v[66:69]
	s_setprio 1
	s_barrier
	s_add_i32 s79, s71, s62
	v_lshl_add_u64 v[186:187], s[54:55], 0, v[156:157]
	s_mov_b32 m0, s79
	ds_read_b128 v[178:181], v192 offset:16384
	ds_read_b128 v[182:185], v192 offset:17408
	ds_read_b128 v[194:197], v192 offset:18432
	ds_read_b128 v[200:203], v192 offset:19456
	ds_read_b128 v[204:207], v192 offset:20480
	ds_read_b128 v[208:211], v192 offset:21504
	ds_read_b128 v[212:215], v192 offset:22528
	ds_read_b128 v[216:219], v192 offset:23552
	global_load_lds_dwordx4 v[186:187], off
	s_add_i32 m0, s79, 0x2000
	s_add_u32 s80, s54, 0x40000
	v_lshl_add_u64 v[220:221], s[54:55], 0, v[160:161]
	s_addc_u32 s81, s55, 0
	s_add_i32 s79, s72, s62
	global_load_lds_dwordx4 v[220:221], off
	v_lshl_add_u64 v[222:223], s[80:81], 0, v[156:157]
	s_mov_b32 m0, s79
	v_lshl_add_u64 v[224:225], s[56:57], 0, v[158:159]
	global_load_lds_dwordx4 v[222:223], off
	v_lshl_add_u64 v[222:223], s[80:81], 0, v[160:161]
	s_add_i32 m0, s79, 0x2000
	s_nop 0
	global_load_lds_dwordx4 v[222:223], off
	v_lshl_add_u64 v[222:223], s[56:57], 0, v[154:155]
	s_mov_b32 m0, s11
	s_nop 0
	global_load_lds_dwordx4 v[222:223], off
	s_mov_b32 m0, s63
	s_nop 0
	global_load_lds_dwordx4 v[224:225], off
	s_waitcnt vmcnt(8)
	s_waitcnt lgkmcnt(0)
	s_barrier
	s_setprio 0
	s_waitcnt lgkmcnt(0)
	v_mfma_f32_16x16x32_bf16 v[62:65], v[130:133], v[178:181], v[62:65]
	v_mfma_f32_16x16x32_bf16 v[58:61], v[138:141], v[178:181], v[58:61]
	v_mfma_f32_16x16x32_bf16 v[46:49], v[130:133], v[194:197], v[46:49]
	v_mfma_f32_16x16x32_bf16 v[42:45], v[138:141], v[194:197], v[42:45]
	v_mfma_f32_16x16x32_bf16 v[30:33], v[130:133], v[204:207], v[30:33]
	v_mfma_f32_16x16x32_bf16 v[26:29], v[138:141], v[204:207], v[26:29]
	v_mfma_f32_16x16x32_bf16 v[14:17], v[130:133], v[212:215], v[14:17]
	v_mfma_f32_16x16x32_bf16 v[10:13], v[138:141], v[212:215], v[10:13]
	v_mfma_f32_16x16x32_bf16 v[62:65], v[134:137], v[182:185], v[62:65]
	v_mfma_f32_16x16x32_bf16 v[58:61], v[142:145], v[182:185], v[58:61]
	v_mfma_f32_16x16x32_bf16 v[46:49], v[134:137], v[200:203], v[46:49]
	v_mfma_f32_16x16x32_bf16 v[42:45], v[142:145], v[200:203], v[42:45]
	v_mfma_f32_16x16x32_bf16 v[30:33], v[134:137], v[208:211], v[30:33]
	v_mfma_f32_16x16x32_bf16 v[26:29], v[142:145], v[208:211], v[26:29]
	v_mfma_f32_16x16x32_bf16 v[14:17], v[134:137], v[216:219], v[14:17]
	v_mfma_f32_16x16x32_bf16 v[10:13], v[142:145], v[216:219], v[10:13]
	s_setprio 1
	s_setprio 0
	v_mfma_f32_16x16x32_bf16 v[54:57], v[146:149], v[178:181], v[54:57]
	v_mfma_f32_16x16x32_bf16 v[50:53], v[170:173], v[178:181], v[50:53]
	v_mfma_f32_16x16x32_bf16 v[38:41], v[146:149], v[194:197], v[38:41]
	v_mfma_f32_16x16x32_bf16 v[34:37], v[170:173], v[194:197], v[34:37]
	v_mfma_f32_16x16x32_bf16 v[22:25], v[146:149], v[204:207], v[22:25]
	v_mfma_f32_16x16x32_bf16 v[18:21], v[170:173], v[204:207], v[18:21]
	v_mfma_f32_16x16x32_bf16 v[6:9], v[146:149], v[212:215], v[6:9]
	v_mfma_f32_16x16x32_bf16 v[2:5], v[170:173], v[212:215], v[2:5]
	v_mfma_f32_16x16x32_bf16 v[54:57], v[150:153], v[182:185], v[54:57]
	v_mfma_f32_16x16x32_bf16 v[50:53], v[174:177], v[182:185], v[50:53]
	v_mfma_f32_16x16x32_bf16 v[38:41], v[150:153], v[200:203], v[38:41]
	v_mfma_f32_16x16x32_bf16 v[34:37], v[174:177], v[200:203], v[34:37]
	v_mfma_f32_16x16x32_bf16 v[22:25], v[150:153], v[208:211], v[22:25]
	v_mfma_f32_16x16x32_bf16 v[18:21], v[174:177], v[208:211], v[18:21]
	v_mfma_f32_16x16x32_bf16 v[6:9], v[150:153], v[216:219], v[6:9]
	v_mfma_f32_16x16x32_bf16 v[2:5], v[174:177], v[216:219], v[2:5]
	s_setprio 1
	s_barrier
	s_add_i32 s79, 0, 0x18000
	s_add_i32 s80, 0, 0x1c000
	v_add_u32_e32 v142, s79, v188
	v_add_u32_e32 v174, s80, v188
	ds_read_b128 v[130:133], v142
	ds_read_b128 v[134:137], v142 offset:1024
	ds_read_b128 v[138:141], v142 offset:2048
	ds_read_b128 v[142:145], v142 offset:3072
	ds_read_b128 v[146:149], v174
	ds_read_b128 v[150:153], v174 offset:1024
	ds_read_b128 v[170:173], v174 offset:2048
	ds_read_b128 v[174:177], v174 offset:3072
	s_add_u32 s56, s56, 0x40000
	s_addc_u32 s57, s57, 0
	s_mov_b32 m0, s64
	v_lshl_add_u64 v[226:227], s[56:57], 0, v[154:155]
	ds_read_b128 v[178:181], v192 offset:32768
	ds_read_b128 v[182:185], v192 offset:33792
	ds_read_b128 v[194:197], v192 offset:34816
	ds_read_b128 v[200:203], v192 offset:35840
	ds_read_b128 v[204:207], v192 offset:36864
	ds_read_b128 v[208:211], v192 offset:37888
	ds_read_b128 v[212:215], v192 offset:38912
	ds_read_b128 v[216:219], v192 offset:39936
	global_load_lds_dwordx4 v[226:227], off
	v_lshl_add_u64 v[226:227], s[56:57], 0, v[158:159]
	s_mov_b32 m0, s65
	s_nop 0
	global_load_lds_dwordx4 v[226:227], off
	s_waitcnt vmcnt(8)
	s_waitcnt lgkmcnt(0)
	s_barrier
	s_setprio 0
	s_waitcnt lgkmcnt(0)
	v_mfma_f32_16x16x32_bf16 v[126:129], v[130:133], v[178:181], v[126:129]
	v_mfma_f32_16x16x32_bf16 v[122:125], v[138:141], v[178:181], v[122:125]
	v_mfma_f32_16x16x32_bf16 v[110:113], v[130:133], v[194:197], v[110:113]
	v_mfma_f32_16x16x32_bf16 v[106:109], v[138:141], v[194:197], v[106:109]
	v_mfma_f32_16x16x32_bf16 v[94:97], v[130:133], v[204:207], v[94:97]
	v_mfma_f32_16x16x32_bf16 v[90:93], v[138:141], v[204:207], v[90:93]
	v_mfma_f32_16x16x32_bf16 v[78:81], v[130:133], v[212:215], v[78:81]
	v_mfma_f32_16x16x32_bf16 v[74:77], v[138:141], v[212:215], v[74:77]
	v_mfma_f32_16x16x32_bf16 v[126:129], v[134:137], v[182:185], v[126:129]
	v_mfma_f32_16x16x32_bf16 v[122:125], v[142:145], v[182:185], v[122:125]
	v_mfma_f32_16x16x32_bf16 v[110:113], v[134:137], v[200:203], v[110:113]
	v_mfma_f32_16x16x32_bf16 v[106:109], v[142:145], v[200:203], v[106:109]
	v_mfma_f32_16x16x32_bf16 v[94:97], v[134:137], v[208:211], v[94:97]
	v_mfma_f32_16x16x32_bf16 v[90:93], v[142:145], v[208:211], v[90:93]
	v_mfma_f32_16x16x32_bf16 v[78:81], v[134:137], v[216:219], v[78:81]
	v_mfma_f32_16x16x32_bf16 v[74:77], v[142:145], v[216:219], v[74:77]
	s_setprio 1
	s_setprio 0
	v_mfma_f32_16x16x32_bf16 v[118:121], v[146:149], v[178:181], v[118:121]
	v_mfma_f32_16x16x32_bf16 v[114:117], v[170:173], v[178:181], v[114:117]
	v_mfma_f32_16x16x32_bf16 v[102:105], v[146:149], v[194:197], v[102:105]
	v_mfma_f32_16x16x32_bf16 v[98:101], v[170:173], v[194:197], v[98:101]
	v_mfma_f32_16x16x32_bf16 v[86:89], v[146:149], v[204:207], v[86:89]
	v_mfma_f32_16x16x32_bf16 v[82:85], v[170:173], v[204:207], v[82:85]
	v_mfma_f32_16x16x32_bf16 v[70:73], v[146:149], v[212:215], v[70:73]
	v_mfma_f32_16x16x32_bf16 v[66:69], v[170:173], v[212:215], v[66:69]
	v_mfma_f32_16x16x32_bf16 v[118:121], v[150:153], v[182:185], v[118:121]
	v_mfma_f32_16x16x32_bf16 v[114:117], v[174:177], v[182:185], v[114:117]
	v_mfma_f32_16x16x32_bf16 v[102:105], v[150:153], v[200:203], v[102:105]
	v_mfma_f32_16x16x32_bf16 v[98:101], v[174:177], v[200:203], v[98:101]
	v_mfma_f32_16x16x32_bf16 v[86:89], v[150:153], v[208:211], v[86:89]
	v_mfma_f32_16x16x32_bf16 v[82:85], v[174:177], v[208:211], v[82:85]
	v_mfma_f32_16x16x32_bf16 v[70:73], v[150:153], v[216:219], v[70:73]
	v_mfma_f32_16x16x32_bf16 v[66:69], v[174:177], v[216:219], v[66:69]
	s_setprio 1
	s_barrier
	s_add_i32 s56, s79, s62
	v_lshl_add_u64 v[186:187], v[186:187], 0, s[18:19]
	s_mov_b32 m0, s56
	ds_read_b128 v[178:181], v192 offset:49152
	ds_read_b128 v[182:185], v192 offset:50176
	ds_read_b128 v[194:197], v192 offset:51200
	ds_read_b128 v[200:203], v192 offset:52224
	ds_read_b128 v[204:207], v192 offset:53248
	ds_read_b128 v[208:211], v192 offset:54272
	ds_read_b128 v[212:215], v192 offset:55296
	ds_read_b128 v[216:219], v192 offset:56320
	global_load_lds_dwordx4 v[186:187], off
	s_add_i32 m0, s56, 0x2000
	s_add_u32 s54, s54, 0x40080
	v_lshl_add_u64 v[186:187], v[220:221], 0, s[18:19]
	s_addc_u32 s55, s55, 0
	s_add_i32 s56, s80, s62
	global_load_lds_dwordx4 v[186:187], off
	v_lshl_add_u64 v[186:187], s[54:55], 0, v[156:157]
	s_mov_b32 m0, s56
	s_nop 0
	global_load_lds_dwordx4 v[186:187], off
	v_lshl_add_u64 v[186:187], s[54:55], 0, v[160:161]
	s_add_i32 m0, s56, 0x2000
	s_nop 0
	global_load_lds_dwordx4 v[186:187], off
	v_lshl_add_u64 v[186:187], v[222:223], 0, s[18:19]
	s_mov_b32 m0, s67
	s_nop 0
	global_load_lds_dwordx4 v[186:187], off
	v_lshl_add_u64 v[186:187], v[224:225], 0, s[18:19]
	s_mov_b32 m0, s68
	s_nop 0
	global_load_lds_dwordx4 v[186:187], off
	s_waitcnt vmcnt(8)
	s_waitcnt lgkmcnt(0)
	s_barrier
	s_setprio 0
	s_waitcnt lgkmcnt(0)
	v_mfma_f32_16x16x32_bf16 v[62:65], v[130:133], v[178:181], v[62:65]
	v_mfma_f32_16x16x32_bf16 v[58:61], v[138:141], v[178:181], v[58:61]
	v_mfma_f32_16x16x32_bf16 v[46:49], v[130:133], v[194:197], v[46:49]
	v_mfma_f32_16x16x32_bf16 v[42:45], v[138:141], v[194:197], v[42:45]
	v_mfma_f32_16x16x32_bf16 v[30:33], v[130:133], v[204:207], v[30:33]
	v_mfma_f32_16x16x32_bf16 v[26:29], v[138:141], v[204:207], v[26:29]
	v_mfma_f32_16x16x32_bf16 v[14:17], v[130:133], v[212:215], v[14:17]
	v_mfma_f32_16x16x32_bf16 v[10:13], v[138:141], v[212:215], v[10:13]
	v_mfma_f32_16x16x32_bf16 v[62:65], v[134:137], v[182:185], v[62:65]
	v_mfma_f32_16x16x32_bf16 v[58:61], v[142:145], v[182:185], v[58:61]
	v_mfma_f32_16x16x32_bf16 v[46:49], v[134:137], v[200:203], v[46:49]
	v_mfma_f32_16x16x32_bf16 v[42:45], v[142:145], v[200:203], v[42:45]
	v_mfma_f32_16x16x32_bf16 v[30:33], v[134:137], v[208:211], v[30:33]
	v_mfma_f32_16x16x32_bf16 v[26:29], v[142:145], v[208:211], v[26:29]
	v_mfma_f32_16x16x32_bf16 v[14:17], v[134:137], v[216:219], v[14:17]
	v_mfma_f32_16x16x32_bf16 v[10:13], v[142:145], v[216:219], v[10:13]
	s_setprio 1
	s_setprio 0
	v_mfma_f32_16x16x32_bf16 v[54:57], v[146:149], v[178:181], v[54:57]
	v_mfma_f32_16x16x32_bf16 v[50:53], v[170:173], v[178:181], v[50:53]
	v_mfma_f32_16x16x32_bf16 v[38:41], v[146:149], v[194:197], v[38:41]
	v_mfma_f32_16x16x32_bf16 v[34:37], v[170:173], v[194:197], v[34:37]
	v_mfma_f32_16x16x32_bf16 v[22:25], v[146:149], v[204:207], v[22:25]
	v_mfma_f32_16x16x32_bf16 v[18:21], v[170:173], v[204:207], v[18:21]
	v_mfma_f32_16x16x32_bf16 v[6:9], v[146:149], v[212:215], v[6:9]
	v_mfma_f32_16x16x32_bf16 v[2:5], v[170:173], v[212:215], v[2:5]
	v_mfma_f32_16x16x32_bf16 v[54:57], v[150:153], v[182:185], v[54:57]
	v_mfma_f32_16x16x32_bf16 v[50:53], v[174:177], v[182:185], v[50:53]
	v_mfma_f32_16x16x32_bf16 v[38:41], v[150:153], v[200:203], v[38:41]
	v_mfma_f32_16x16x32_bf16 v[34:37], v[174:177], v[200:203], v[34:37]
	v_mfma_f32_16x16x32_bf16 v[22:25], v[150:153], v[208:211], v[22:25]
	v_mfma_f32_16x16x32_bf16 v[18:21], v[174:177], v[208:211], v[18:21]
	v_mfma_f32_16x16x32_bf16 v[6:9], v[150:153], v[216:219], v[6:9]
	v_mfma_f32_16x16x32_bf16 v[2:5], v[174:177], v[216:219], v[2:5]
	s_setprio 1
	s_barrier
	s_add_i32 s78, s78, 2
	s_add_u32 s52, s52, 0x100
	s_addc_u32 s53, s53, 0
	s_add_u32 s76, s76, 0x100
	s_addc_u32 s77, s77, 0
	s_cmp_gt_u32 s78, 13
	s_cbranch_scc0 .LBB0_557
	s_and_b64 vcc, exec, s[20:21]
	s_cbranch_vccz .LBB0_560
	s_barrier

.LBB0_580:
	s_setprio 0
	s_cmp_gt_i32 s35, 5
	s_cselect_b64 s[4:5], -1, 0
	s_and_b64 s[6:7], s[8:9], s[4:5]
	s_andn2_b64 vcc, exec, s[6:7]
	s_cbranch_vccnz .LBB0_629
	s_waitcnt vmcnt(0)
	v_cmp_eq_u32_e32 vcc, 0, v0
	s_waitcnt vmcnt(0) lgkmcnt(0)
	s_barrier
	s_and_saveexec_b64 s[6:7], vcc
	s_cbranch_execz .LBB0_628
	v_mov_b32_e32 v1, s33
	s_waitcnt vmcnt(0) expcnt(0) lgkmcnt(0)
	ds_read_b32 v3, v1
	ds_read_b32 v1, v1 offset:4
	s_waitcnt lgkmcnt(1)
	v_cmp_ne_u32_e32 vcc, 0, v3
	s_cbranch_vccnz .LBB0_597
	s_load_dwordx2 s[12:13], s[42:43], 0x4
	s_add_u32 s8, s38, 0x4200
	s_addc_u32 s9, s39, 0
	s_add_u32 s10, s38, 0x4400
	s_addc_u32 s11, s39, 0
	s_waitcnt lgkmcnt(0)
	s_mul_i32 s66, s12, s30
	s_add_u32 s12, s38, 0x4500
	s_mul_i32 s66, s66, s13
	s_addc_u32 s13, s39, 0
	s_add_u32 s14, s38, 0x4600
	s_addc_u32 s15, s39, 0
	s_add_u32 s18, s38, 0x4700
	s_addc_u32 s19, s39, 0
	s_add_u32 s20, s38, 0x4800
	s_addc_u32 s21, s39, 0
	s_add_u32 s22, s38, 0x4900
	s_addc_u32 s23, s39, 0
	s_add_u32 s24, s38, 0x4a00
	s_addc_u32 s25, s39, 0
	s_add_u32 s26, s38, 0x4b00
	s_addc_u32 s27, s39, 0
	s_add_u32 s28, s38, 0x4c00
	s_addc_u32 s29, s39, 0
	s_add_u32 s46, s38, 0x4d00
	s_addc_u32 s47, s39, 0
	s_add_u32 s48, s38, 0x4e00
	s_addc_u32 s49, s39, 0
	s_add_u32 s50, s38, 0x4f00
	s_addc_u32 s51, s39, 0
	s_add_u32 s52, s38, 0x5000
	s_addc_u32 s53, s39, 0
	s_add_u32 s54, s38, 0x5100
	s_addc_u32 s55, s39, 0
	s_add_u32 s56, s38, 0x5200
	s_addc_u32 s57, s39, 0
	s_add_u32 s58, s38, 0x5300
	s_addc_u32 s59, s39, 0
	s_mov_b32 s67, 1
	v_mov_b32_e32 v17, 0
	s_branch .LBB0_585

.LBB0_713:
	ds_read_b128 v[130:133], v243
	ds_read_b128 v[134:137], v243 offset:1024
	ds_read_b128 v[138:141], v243 offset:2048
	ds_read_b128 v[142:145], v243 offset:3072
	ds_read_b128 v[146:149], v244
	ds_read_b128 v[150:153], v244 offset:1024
	ds_read_b128 v[154:157], v244 offset:2048
	ds_read_b128 v[158:161], v244 offset:3072
	s_add_u32 s62, s12, 0xfffc0080
	s_addc_u32 s63, s13, -1
	s_cmp_eq_u32 s95, 12
	s_cselect_b32 s65, s57, s63
	s_cselect_b32 s64, s67, s62
	s_cselect_b32 s63, s55, s94
	s_cselect_b32 s62, s92, s93
	v_lshl_add_u64 v[194:195], s[12:13], 0, v[216:217]
	s_add_i32 m0, s25, 0xc000
	ds_read_b128 v[162:165], v245
	ds_read_b128 v[166:169], v245 offset:1024
	ds_read_b128 v[170:173], v245 offset:2048
	ds_read_b128 v[174:177], v245 offset:3072
	ds_read_b128 v[178:181], v245 offset:4096
	ds_read_b128 v[182:185], v245 offset:5120
	ds_read_b128 v[186:189], v245 offset:6144
	ds_read_b128 v[190:193], v245 offset:7168
	global_load_lds_dwordx4 v[194:195], off
	v_lshl_add_u64 v[194:195], s[12:13], 0, v[218:219]
	s_add_i32 m0, s25, 0xe000
	s_nop 0
	global_load_lds_dwordx4 v[194:195], off
	s_waitcnt vmcnt(8)
	s_waitcnt lgkmcnt(0)
	s_barrier
	s_setprio 0
	s_waitcnt lgkmcnt(0)
	v_mfma_f32_16x16x32_bf16 v[126:129], v[130:133], v[162:165], v[126:129]
	v_mfma_f32_16x16x32_bf16 v[122:125], v[138:141], v[162:165], v[122:125]
	v_mfma_f32_16x16x32_bf16 v[110:113], v[130:133], v[170:173], v[110:113]
	v_mfma_f32_16x16x32_bf16 v[106:109], v[138:141], v[170:173], v[106:109]
	v_mfma_f32_16x16x32_bf16 v[94:97], v[130:133], v[178:181], v[94:97]
	v_mfma_f32_16x16x32_bf16 v[90:93], v[138:141], v[178:181], v[90:93]
	v_mfma_f32_16x16x32_bf16 v[78:81], v[130:133], v[186:189], v[78:81]
	v_mfma_f32_16x16x32_bf16 v[74:77], v[138:141], v[186:189], v[74:77]
	v_mfma_f32_16x16x32_bf16 v[126:129], v[134:137], v[166:169], v[126:129]
	v_mfma_f32_16x16x32_bf16 v[122:125], v[142:145], v[166:169], v[122:125]
	v_mfma_f32_16x16x32_bf16 v[110:113], v[134:137], v[174:177], v[110:113]
	v_mfma_f32_16x16x32_bf16 v[106:109], v[142:145], v[174:177], v[106:109]
	v_mfma_f32_16x16x32_bf16 v[94:97], v[134:137], v[182:185], v[94:97]
	v_mfma_f32_16x16x32_bf16 v[90:93], v[142:145], v[182:185], v[90:93]
	v_mfma_f32_16x16x32_bf16 v[78:81], v[134:137], v[190:193], v[78:81]
	v_mfma_f32_16x16x32_bf16 v[74:77], v[142:145], v[190:193], v[74:77]
	s_setprio 1
	s_setprio 0
	v_mfma_f32_16x16x32_bf16 v[118:121], v[146:149], v[162:165], v[118:121]
	v_mfma_f32_16x16x32_bf16 v[114:117], v[154:157], v[162:165], v[114:117]
	v_mfma_f32_16x16x32_bf16 v[102:105], v[146:149], v[170:173], v[102:105]
	v_mfma_f32_16x16x32_bf16 v[98:101], v[154:157], v[170:173], v[98:101]
	v_mfma_f32_16x16x32_bf16 v[86:89], v[146:149], v[178:181], v[86:89]
	v_mfma_f32_16x16x32_bf16 v[82:85], v[154:157], v[178:181], v[82:85]
	v_mfma_f32_16x16x32_bf16 v[70:73], v[146:149], v[186:189], v[70:73]
	v_mfma_f32_16x16x32_bf16 v[66:69], v[154:157], v[186:189], v[66:69]
	v_mfma_f32_16x16x32_bf16 v[118:121], v[150:153], v[166:169], v[118:121]
	v_mfma_f32_16x16x32_bf16 v[114:117], v[158:161], v[166:169], v[114:117]
	v_mfma_f32_16x16x32_bf16 v[102:105], v[150:153], v[174:177], v[102:105]
	v_mfma_f32_16x16x32_bf16 v[98:101], v[158:161], v[174:177], v[98:101]
	v_mfma_f32_16x16x32_bf16 v[86:89], v[150:153], v[182:185], v[86:89]
	v_mfma_f32_16x16x32_bf16 v[82:85], v[158:161], v[182:185], v[82:85]
	v_mfma_f32_16x16x32_bf16 v[70:73], v[150:153], v[190:193], v[70:73]
	v_mfma_f32_16x16x32_bf16 v[66:69], v[158:161], v[190:193], v[66:69]
	s_setprio 1
	s_barrier
	s_add_i32 s96, s85, s73
	v_lshl_add_u64 v[194:195], s[62:63], 0, v[202:203]
	s_mov_b32 m0, s96
	ds_read_b128 v[162:165], v245 offset:16384
	ds_read_b128 v[166:169], v245 offset:17408
	ds_read_b128 v[170:173], v245 offset:18432
	ds_read_b128 v[174:177], v245 offset:19456
	ds_read_b128 v[178:181], v245 offset:20480
	ds_read_b128 v[182:185], v245 offset:21504
	ds_read_b128 v[186:189], v245 offset:22528
	ds_read_b128 v[190:193], v245 offset:23552
	global_load_lds_dwordx4 v[194:195], off
	s_add_i32 m0, s96, 0x2000
	s_add_u32 s96, s62, 0x40000
	v_lshl_add_u64 v[196:197], s[62:63], 0, v[206:207]
	s_addc_u32 s97, s63, 0
	s_add_i32 vcc_lo, s86, s73
	global_load_lds_dwordx4 v[196:197], off
	v_lshl_add_u64 v[220:221], s[96:97], 0, v[202:203]
	s_mov_b32 m0, vcc_lo
	v_lshl_add_u64 v[222:223], s[64:65], 0, v[204:205]
	global_load_lds_dwordx4 v[220:221], off
	v_lshl_add_u64 v[220:221], s[96:97], 0, v[206:207]
	s_add_i32 m0, vcc_lo, 0x2000
	s_nop 0
	global_load_lds_dwordx4 v[220:221], off
	v_lshl_add_u64 v[220:221], s[64:65], 0, v[200:201]
	s_mov_b32 m0, s25
	s_nop 0
	global_load_lds_dwordx4 v[220:221], off
	s_mov_b32 m0, s74
	s_nop 0
	global_load_lds_dwordx4 v[222:223], off
	s_waitcnt vmcnt(8)
	s_waitcnt lgkmcnt(0)
	s_barrier
	s_setprio 0
	s_waitcnt lgkmcnt(0)
	v_mfma_f32_16x16x32_bf16 v[62:65], v[130:133], v[162:165], v[62:65]
	v_mfma_f32_16x16x32_bf16 v[58:61], v[138:141], v[162:165], v[58:61]
	v_mfma_f32_16x16x32_bf16 v[46:49], v[130:133], v[170:173], v[46:49]
	v_mfma_f32_16x16x32_bf16 v[42:45], v[138:141], v[170:173], v[42:45]
	v_mfma_f32_16x16x32_bf16 v[30:33], v[130:133], v[178:181], v[30:33]
	v_mfma_f32_16x16x32_bf16 v[26:29], v[138:141], v[178:181], v[26:29]
	v_mfma_f32_16x16x32_bf16 v[14:17], v[130:133], v[186:189], v[14:17]
	v_mfma_f32_16x16x32_bf16 v[10:13], v[138:141], v[186:189], v[10:13]
	v_mfma_f32_16x16x32_bf16 v[62:65], v[134:137], v[166:169], v[62:65]
	v_mfma_f32_16x16x32_bf16 v[58:61], v[142:145], v[166:169], v[58:61]
	v_mfma_f32_16x16x32_bf16 v[46:49], v[134:137], v[174:177], v[46:49]
	v_mfma_f32_16x16x32_bf16 v[42:45], v[142:145], v[174:177], v[42:45]
	v_mfma_f32_16x16x32_bf16 v[30:33], v[134:137], v[182:185], v[30:33]
	v_mfma_f32_16x16x32_bf16 v[26:29], v[142:145], v[182:185], v[26:29]
	v_mfma_f32_16x16x32_bf16 v[14:17], v[134:137], v[190:193], v[14:17]
	v_mfma_f32_16x16x32_bf16 v[10:13], v[142:145], v[190:193], v[10:13]
	s_setprio 1
	s_setprio 0
	v_mfma_f32_16x16x32_bf16 v[54:57], v[146:149], v[162:165], v[54:57]
	v_mfma_f32_16x16x32_bf16 v[50:53], v[154:157], v[162:165], v[50:53]
	v_mfma_f32_16x16x32_bf16 v[38:41], v[146:149], v[170:173], v[38:41]
	v_mfma_f32_16x16x32_bf16 v[34:37], v[154:157], v[170:173], v[34:37]
	v_mfma_f32_16x16x32_bf16 v[22:25], v[146:149], v[178:181], v[22:25]
	v_mfma_f32_16x16x32_bf16 v[18:21], v[154:157], v[178:181], v[18:21]
	v_mfma_f32_16x16x32_bf16 v[6:9], v[146:149], v[186:189], v[6:9]
	v_mfma_f32_16x16x32_bf16 v[2:5], v[154:157], v[186:189], v[2:5]
	v_mfma_f32_16x16x32_bf16 v[54:57], v[150:153], v[166:169], v[54:57]
	v_mfma_f32_16x16x32_bf16 v[50:53], v[158:161], v[166:169], v[50:53]
	v_mfma_f32_16x16x32_bf16 v[38:41], v[150:153], v[174:177], v[38:41]
	v_mfma_f32_16x16x32_bf16 v[34:37], v[158:161], v[174:177], v[34:37]
	v_mfma_f32_16x16x32_bf16 v[22:25], v[150:153], v[182:185], v[22:25]
	v_mfma_f32_16x16x32_bf16 v[18:21], v[158:161], v[182:185], v[18:21]
	v_mfma_f32_16x16x32_bf16 v[6:9], v[150:153], v[190:193], v[6:9]
	v_mfma_f32_16x16x32_bf16 v[2:5], v[158:161], v[190:193], v[2:5]
	s_setprio 1
	s_barrier
	s_add_i32 s96, 0, 0x18000
	s_add_i32 s97, 0, 0x1c000
	v_add_u32_e32 v142, s96, v199
	v_add_u32_e32 v158, s97, v199
	ds_read_b128 v[130:133], v142
	ds_read_b128 v[134:137], v142 offset:1024
	ds_read_b128 v[138:141], v142 offset:2048
	ds_read_b128 v[142:145], v142 offset:3072
	ds_read_b128 v[146:149], v158
	ds_read_b128 v[150:153], v158 offset:1024
	ds_read_b128 v[154:157], v158 offset:2048
	ds_read_b128 v[158:161], v158 offset:3072
	s_add_u32 s64, s64, 0x40000
	s_addc_u32 s65, s65, 0
	s_mov_b32 m0, s75
	v_lshl_add_u64 v[224:225], s[64:65], 0, v[200:201]
	ds_read_b128 v[162:165], v245 offset:32768
	ds_read_b128 v[166:169], v245 offset:33792
	ds_read_b128 v[170:173], v245 offset:34816
	ds_read_b128 v[174:177], v245 offset:35840
	ds_read_b128 v[178:181], v245 offset:36864
	ds_read_b128 v[182:185], v245 offset:37888
	ds_read_b128 v[186:189], v245 offset:38912
	ds_read_b128 v[190:193], v245 offset:39936
	global_load_lds_dwordx4 v[224:225], off
	v_lshl_add_u64 v[224:225], s[64:65], 0, v[204:205]
	s_mov_b32 m0, s76
	s_nop 0
	global_load_lds_dwordx4 v[224:225], off
	s_waitcnt vmcnt(8)
	s_waitcnt lgkmcnt(0)
	s_barrier
	s_setprio 0
	s_waitcnt lgkmcnt(0)
	v_mfma_f32_16x16x32_bf16 v[126:129], v[130:133], v[162:165], v[126:129]
	v_mfma_f32_16x16x32_bf16 v[122:125], v[138:141], v[162:165], v[122:125]
	v_mfma_f32_16x16x32_bf16 v[110:113], v[130:133], v[170:173], v[110:113]
	v_mfma_f32_16x16x32_bf16 v[106:109], v[138:141], v[170:173], v[106:109]
	v_mfma_f32_16x16x32_bf16 v[94:97], v[130:133], v[178:181], v[94:97]
	v_mfma_f32_16x16x32_bf16 v[90:93], v[138:141], v[178:181], v[90:93]
	v_mfma_f32_16x16x32_bf16 v[78:81], v[130:133], v[186:189], v[78:81]
	v_mfma_f32_16x16x32_bf16 v[74:77], v[138:141], v[186:189], v[74:77]
	v_mfma_f32_16x16x32_bf16 v[126:129], v[134:137], v[166:169], v[126:129]
	v_mfma_f32_16x16x32_bf16 v[122:125], v[142:145], v[166:169], v[122:125]
	v_mfma_f32_16x16x32_bf16 v[110:113], v[134:137], v[174:177], v[110:113]
	v_mfma_f32_16x16x32_bf16 v[106:109], v[142:145], v[174:177], v[106:109]
	v_mfma_f32_16x16x32_bf16 v[94:97], v[134:137], v[182:185], v[94:97]
	v_mfma_f32_16x16x32_bf16 v[90:93], v[142:145], v[182:185], v[90:93]
	v_mfma_f32_16x16x32_bf16 v[78:81], v[134:137], v[190:193], v[78:81]
	v_mfma_f32_16x16x32_bf16 v[74:77], v[142:145], v[190:193], v[74:77]
	s_setprio 1
	s_setprio 0
	v_mfma_f32_16x16x32_bf16 v[118:121], v[146:149], v[162:165], v[118:121]
	v_mfma_f32_16x16x32_bf16 v[114:117], v[154:157], v[162:165], v[114:117]
	v_mfma_f32_16x16x32_bf16 v[102:105], v[146:149], v[170:173], v[102:105]
	v_mfma_f32_16x16x32_bf16 v[98:101], v[154:157], v[170:173], v[98:101]
	v_mfma_f32_16x16x32_bf16 v[86:89], v[146:149], v[178:181], v[86:89]
	v_mfma_f32_16x16x32_bf16 v[82:85], v[154:157], v[178:181], v[82:85]
	v_mfma_f32_16x16x32_bf16 v[70:73], v[146:149], v[186:189], v[70:73]
	v_mfma_f32_16x16x32_bf16 v[66:69], v[154:157], v[186:189], v[66:69]
	v_mfma_f32_16x16x32_bf16 v[118:121], v[150:153], v[166:169], v[118:121]
	v_mfma_f32_16x16x32_bf16 v[114:117], v[158:161], v[166:169], v[114:117]
	v_mfma_f32_16x16x32_bf16 v[102:105], v[150:153], v[174:177], v[102:105]
	v_mfma_f32_16x16x32_bf16 v[98:101], v[158:161], v[174:177], v[98:101]
	v_mfma_f32_16x16x32_bf16 v[86:89], v[150:153], v[182:185], v[86:89]
	v_mfma_f32_16x16x32_bf16 v[82:85], v[158:161], v[182:185], v[82:85]
	v_mfma_f32_16x16x32_bf16 v[70:73], v[150:153], v[190:193], v[70:73]
	v_mfma_f32_16x16x32_bf16 v[66:69], v[158:161], v[190:193], v[66:69]
	s_setprio 1
	s_barrier
	s_add_i32 s64, s96, s73
	v_lshl_add_u64 v[194:195], v[194:195], 0, s[26:27]
	s_mov_b32 m0, s64
	ds_read_b128 v[162:165], v245 offset:49152
	ds_read_b128 v[166:169], v245 offset:50176
	ds_read_b128 v[170:173], v245 offset:51200
	ds_read_b128 v[174:177], v245 offset:52224
	ds_read_b128 v[178:181], v245 offset:53248
	ds_read_b128 v[182:185], v245 offset:54272
	ds_read_b128 v[186:189], v245 offset:55296
	ds_read_b128 v[190:193], v245 offset:56320
	global_load_lds_dwordx4 v[194:195], off
	s_add_i32 m0, s64, 0x2000
	s_add_u32 s62, s62, 0x40080
	v_lshl_add_u64 v[194:195], v[196:197], 0, s[26:27]
	s_addc_u32 s63, s63, 0
	s_add_i32 s64, s97, s73
	global_load_lds_dwordx4 v[194:195], off
	v_lshl_add_u64 v[194:195], s[62:63], 0, v[202:203]
	s_mov_b32 m0, s64
	s_nop 0
	global_load_lds_dwordx4 v[194:195], off
	v_lshl_add_u64 v[194:195], s[62:63], 0, v[206:207]
	s_add_i32 m0, s64, 0x2000
	s_nop 0
	global_load_lds_dwordx4 v[194:195], off
	v_lshl_add_u64 v[194:195], v[220:221], 0, s[26:27]
	s_mov_b32 m0, s77
	s_nop 0
	global_load_lds_dwordx4 v[194:195], off
	v_lshl_add_u64 v[194:195], v[222:223], 0, s[26:27]
	s_mov_b32 m0, s78
	s_nop 0
	global_load_lds_dwordx4 v[194:195], off
	s_waitcnt vmcnt(8)
	s_waitcnt lgkmcnt(0)
	s_barrier
	s_setprio 0
	s_waitcnt lgkmcnt(0)
	v_mfma_f32_16x16x32_bf16 v[62:65], v[130:133], v[162:165], v[62:65]
	v_mfma_f32_16x16x32_bf16 v[58:61], v[138:141], v[162:165], v[58:61]
	v_mfma_f32_16x16x32_bf16 v[46:49], v[130:133], v[170:173], v[46:49]
	v_mfma_f32_16x16x32_bf16 v[42:45], v[138:141], v[170:173], v[42:45]
	v_mfma_f32_16x16x32_bf16 v[30:33], v[130:133], v[178:181], v[30:33]
	v_mfma_f32_16x16x32_bf16 v[26:29], v[138:141], v[178:181], v[26:29]
	v_mfma_f32_16x16x32_bf16 v[14:17], v[130:133], v[186:189], v[14:17]
	v_mfma_f32_16x16x32_bf16 v[10:13], v[138:141], v[186:189], v[10:13]
	v_mfma_f32_16x16x32_bf16 v[62:65], v[134:137], v[166:169], v[62:65]
	v_mfma_f32_16x16x32_bf16 v[58:61], v[142:145], v[166:169], v[58:61]
	v_mfma_f32_16x16x32_bf16 v[46:49], v[134:137], v[174:177], v[46:49]
	v_mfma_f32_16x16x32_bf16 v[42:45], v[142:145], v[174:177], v[42:45]
	v_mfma_f32_16x16x32_bf16 v[30:33], v[134:137], v[182:185], v[30:33]
	v_mfma_f32_16x16x32_bf16 v[26:29], v[142:145], v[182:185], v[26:29]
	v_mfma_f32_16x16x32_bf16 v[14:17], v[134:137], v[190:193], v[14:17]
	v_mfma_f32_16x16x32_bf16 v[10:13], v[142:145], v[190:193], v[10:13]
	s_setprio 1
	s_setprio 0
	v_mfma_f32_16x16x32_bf16 v[54:57], v[146:149], v[162:165], v[54:57]
	v_mfma_f32_16x16x32_bf16 v[50:53], v[154:157], v[162:165], v[50:53]
	v_mfma_f32_16x16x32_bf16 v[38:41], v[146:149], v[170:173], v[38:41]
	v_mfma_f32_16x16x32_bf16 v[34:37], v[154:157], v[170:173], v[34:37]
	v_mfma_f32_16x16x32_bf16 v[22:25], v[146:149], v[178:181], v[22:25]
	v_mfma_f32_16x16x32_bf16 v[18:21], v[154:157], v[178:181], v[18:21]
	v_mfma_f32_16x16x32_bf16 v[6:9], v[146:149], v[186:189], v[6:9]
	v_mfma_f32_16x16x32_bf16 v[2:5], v[154:157], v[186:189], v[2:5]
	v_mfma_f32_16x16x32_bf16 v[54:57], v[150:153], v[166:169], v[54:57]
	v_mfma_f32_16x16x32_bf16 v[50:53], v[158:161], v[166:169], v[50:53]
	v_mfma_f32_16x16x32_bf16 v[38:41], v[150:153], v[174:177], v[38:41]
	v_mfma_f32_16x16x32_bf16 v[34:37], v[158:161], v[174:177], v[34:37]
	v_mfma_f32_16x16x32_bf16 v[22:25], v[150:153], v[182:185], v[22:25]
	v_mfma_f32_16x16x32_bf16 v[18:21], v[158:161], v[182:185], v[18:21]
	v_mfma_f32_16x16x32_bf16 v[6:9], v[150:153], v[190:193], v[6:9]
	v_mfma_f32_16x16x32_bf16 v[2:5], v[158:161], v[190:193], v[2:5]
	s_setprio 1
	s_barrier
	s_add_i32 s95, s95, 2
	s_add_u32 s12, s12, 0x100
	s_addc_u32 s13, s13, 0
	s_add_u32 s93, s93, 0x100
	s_addc_u32 s94, s94, 0
	s_cmp_gt_u32 s95, 13
	s_cbranch_scc0 .LBB0_713
	s_and_b64 vcc, exec, s[28:29]
	s_cbranch_vccz .LBB0_716
	s_barrier

.LBB0_798:
	s_setprio 0
	s_cmp_gt_u32 s35, 6
	s_cselect_b64 s[0:1], -1, 0
	s_and_b64 s[0:1], s[14:15], s[0:1]
	s_andn2_b64 vcc, exec, s[0:1]
	s_cbranch_vccnz .LBB0_847
	s_waitcnt vmcnt(0)
	v_cmp_eq_u32_e32 vcc, 0, v0
	s_waitcnt vmcnt(0) lgkmcnt(0)
	s_barrier
	s_and_saveexec_b64 s[0:1], vcc
	s_cbranch_execz .LBB0_846
	v_mov_b32_e32 v1, s33
	s_waitcnt vmcnt(0) expcnt(0) lgkmcnt(0)
	ds_read_b32 v3, v1
	ds_read_b32 v1, v1 offset:4
	s_waitcnt lgkmcnt(1)
	v_cmp_ne_u32_e32 vcc, 0, v3
	s_cbranch_vccnz .LBB0_815
	s_load_dwordx2 s[8:9], s[42:43], 0x4
	s_add_u32 s4, s38, 0x4200
	s_addc_u32 s5, s39, 0
	s_add_u32 s6, s38, 0x4400
	s_addc_u32 s7, s39, 0
	s_waitcnt lgkmcnt(0)
	s_mul_i32 s62, s8, s30
	s_add_u32 s8, s38, 0x4500
	s_mul_i32 s62, s62, s9
	s_addc_u32 s9, s39, 0
	s_add_u32 s10, s38, 0x4600
	s_addc_u32 s11, s39, 0
	s_add_u32 s12, s38, 0x4700
	s_addc_u32 s13, s39, 0
	s_add_u32 s14, s38, 0x4800
	s_addc_u32 s15, s39, 0
	s_add_u32 s18, s38, 0x4900
	s_addc_u32 s19, s39, 0
	s_add_u32 s20, s38, 0x4a00
	s_addc_u32 s21, s39, 0
	s_add_u32 s22, s38, 0x4b00
	s_addc_u32 s23, s39, 0
	s_add_u32 s24, s38, 0x4c00
	s_addc_u32 s25, s39, 0
	s_add_u32 s26, s38, 0x4d00
	s_addc_u32 s27, s39, 0
	s_add_u32 s28, s38, 0x4e00
	s_addc_u32 s29, s39, 0
	s_add_u32 s46, s38, 0x4f00
	s_addc_u32 s47, s39, 0
	s_add_u32 s48, s38, 0x5000
	s_addc_u32 s49, s39, 0
	s_add_u32 s50, s38, 0x5100
	s_addc_u32 s51, s39, 0
	s_add_u32 s52, s38, 0x5200
	s_addc_u32 s53, s39, 0
	s_add_u32 s54, s38, 0x5300
	s_addc_u32 s55, s39, 0
	s_mov_b32 s63, 1
	v_mov_b32_e32 v17, 0
	s_branch .LBB0_803

.LBB0_1200:
	ds_read_b128 v[120:123], v207
	ds_read_b128 v[132:135], v207 offset:1024
	ds_read_b128 v[136:139], v207 offset:2048
	ds_read_b128 v[140:143], v207 offset:3072
	ds_read_b128 v[144:147], v208
	ds_read_b128 v[148:151], v208 offset:1024
	ds_read_b128 v[152:155], v208 offset:2048
	ds_read_b128 v[156:159], v208 offset:3072
	s_add_u32 s34, s28, 0xfffc0080
	s_addc_u32 s35, s29, -1
	s_cmp_eq_u32 s61, 12
	s_cselect_b32 s41, s21, s35
	s_cselect_b32 s40, s57, s34
	s_cselect_b32 s35, s19, s60
	s_cselect_b32 s34, s58, s59
	v_lshl_add_u64 v[222:223], s[28:29], 0, v[190:191]
	s_add_i32 m0, s45, 0xc000
	ds_read_b128 v[160:163], v209
	ds_read_b128 v[164:167], v209 offset:1024
	ds_read_b128 v[168:171], v209 offset:2048
	ds_read_b128 v[172:175], v209 offset:3072
	ds_read_b128 v[176:179], v209 offset:4096
	ds_read_b128 v[210:213], v209 offset:5120
	ds_read_b128 v[214:217], v209 offset:6144
	ds_read_b128 v[218:221], v209 offset:7168
	global_load_lds_dwordx4 v[222:223], off
	v_lshl_add_u64 v[222:223], s[28:29], 0, v[192:193]
	s_add_i32 m0, s45, 0xe000
	s_nop 0
	global_load_lds_dwordx4 v[222:223], off
	s_waitcnt vmcnt(8)
	s_waitcnt lgkmcnt(0)
	s_barrier
	s_setprio 0
	s_waitcnt lgkmcnt(0)
	v_mfma_f32_16x16x32_bf16 v[128:131], v[120:123], v[160:163], v[128:131]
	v_mfma_f32_16x16x32_bf16 v[124:127], v[136:139], v[160:163], v[124:127]
	v_mfma_f32_16x16x32_bf16 v[108:111], v[120:123], v[168:171], v[108:111]
	v_mfma_f32_16x16x32_bf16 v[104:107], v[136:139], v[168:171], v[104:107]
	v_mfma_f32_16x16x32_bf16 v[92:95], v[120:123], v[176:179], v[92:95]
	v_mfma_f32_16x16x32_bf16 v[88:91], v[136:139], v[176:179], v[88:91]
	v_mfma_f32_16x16x32_bf16 v[76:79], v[120:123], v[214:217], v[76:79]
	v_mfma_f32_16x16x32_bf16 v[72:75], v[136:139], v[214:217], v[72:75]
	v_mfma_f32_16x16x32_bf16 v[128:131], v[132:135], v[164:167], v[128:131]
	v_mfma_f32_16x16x32_bf16 v[124:127], v[140:143], v[164:167], v[124:127]
	v_mfma_f32_16x16x32_bf16 v[108:111], v[132:135], v[172:175], v[108:111]
	v_mfma_f32_16x16x32_bf16 v[104:107], v[140:143], v[172:175], v[104:107]
	v_mfma_f32_16x16x32_bf16 v[92:95], v[132:135], v[210:213], v[92:95]
	v_mfma_f32_16x16x32_bf16 v[88:91], v[140:143], v[210:213], v[88:91]
	v_mfma_f32_16x16x32_bf16 v[76:79], v[132:135], v[218:221], v[76:79]
	v_mfma_f32_16x16x32_bf16 v[72:75], v[140:143], v[218:221], v[72:75]
	s_setprio 1
	s_setprio 0
	v_mfma_f32_16x16x32_bf16 v[116:119], v[144:147], v[160:163], v[116:119]
	v_mfma_f32_16x16x32_bf16 v[112:115], v[152:155], v[160:163], v[112:115]
	v_mfma_f32_16x16x32_bf16 v[100:103], v[144:147], v[168:171], v[100:103]
	v_mfma_f32_16x16x32_bf16 v[96:99], v[152:155], v[168:171], v[96:99]
	v_mfma_f32_16x16x32_bf16 v[84:87], v[144:147], v[176:179], v[84:87]
	v_mfma_f32_16x16x32_bf16 v[80:83], v[152:155], v[176:179], v[80:83]
	v_mfma_f32_16x16x32_bf16 v[68:71], v[144:147], v[214:217], v[68:71]
	v_mfma_f32_16x16x32_bf16 v[64:67], v[152:155], v[214:217], v[64:67]
	v_mfma_f32_16x16x32_bf16 v[116:119], v[148:151], v[164:167], v[116:119]
	v_mfma_f32_16x16x32_bf16 v[112:115], v[156:159], v[164:167], v[112:115]
	v_mfma_f32_16x16x32_bf16 v[100:103], v[148:151], v[172:175], v[100:103]
	v_mfma_f32_16x16x32_bf16 v[96:99], v[156:159], v[172:175], v[96:99]
	v_mfma_f32_16x16x32_bf16 v[84:87], v[148:151], v[210:213], v[84:87]
	v_mfma_f32_16x16x32_bf16 v[80:83], v[156:159], v[210:213], v[80:83]
	v_mfma_f32_16x16x32_bf16 v[68:71], v[148:151], v[218:221], v[68:71]
	v_mfma_f32_16x16x32_bf16 v[64:67], v[156:159], v[218:221], v[64:67]
	s_setprio 1
	s_barrier
	s_add_i32 s62, s53, s44
	v_lshl_add_u64 v[222:223], s[34:35], 0, v[182:183]
	s_mov_b32 m0, s62
	ds_read_b128 v[160:163], v209 offset:16384
	ds_read_b128 v[164:167], v209 offset:17408
	ds_read_b128 v[168:171], v209 offset:18432
	ds_read_b128 v[172:175], v209 offset:19456
	ds_read_b128 v[176:179], v209 offset:20480
	ds_read_b128 v[210:213], v209 offset:21504
	ds_read_b128 v[214:217], v209 offset:22528
	ds_read_b128 v[218:221], v209 offset:23552
	global_load_lds_dwordx4 v[222:223], off
	s_add_i32 m0, s62, 0x2000
	s_add_u32 s62, s34, 0x40000
	v_lshl_add_u64 v[224:225], s[34:35], 0, v[186:187]
	s_addc_u32 s63, s35, 0
	s_add_i32 s64, s54, s44
	global_load_lds_dwordx4 v[224:225], off
	v_lshl_add_u64 v[226:227], s[62:63], 0, v[182:183]
	s_mov_b32 m0, s64
	v_lshl_add_u64 v[228:229], s[40:41], 0, v[184:185]
	global_load_lds_dwordx4 v[226:227], off
	v_lshl_add_u64 v[226:227], s[62:63], 0, v[186:187]
	s_add_i32 m0, s64, 0x2000
	s_nop 0
	global_load_lds_dwordx4 v[226:227], off
	v_lshl_add_u64 v[226:227], s[40:41], 0, v[180:181]
	s_mov_b32 m0, s45
	s_nop 0
	global_load_lds_dwordx4 v[226:227], off
	s_mov_b32 m0, s46
	s_nop 0
	global_load_lds_dwordx4 v[228:229], off
	s_waitcnt vmcnt(8)
	s_waitcnt lgkmcnt(0)
	s_barrier
	s_setprio 0
	s_waitcnt lgkmcnt(0)
	v_mfma_f32_16x16x32_bf16 v[60:63], v[120:123], v[160:163], v[60:63]
	v_mfma_f32_16x16x32_bf16 v[56:59], v[136:139], v[160:163], v[56:59]
	v_mfma_f32_16x16x32_bf16 v[44:47], v[120:123], v[168:171], v[44:47]
	v_mfma_f32_16x16x32_bf16 v[40:43], v[136:139], v[168:171], v[40:43]
	v_mfma_f32_16x16x32_bf16 v[28:31], v[120:123], v[176:179], v[28:31]
	v_mfma_f32_16x16x32_bf16 v[24:27], v[136:139], v[176:179], v[24:27]
	v_mfma_f32_16x16x32_bf16 v[12:15], v[120:123], v[214:217], v[12:15]
	v_mfma_f32_16x16x32_bf16 v[8:11], v[136:139], v[214:217], v[8:11]
	v_mfma_f32_16x16x32_bf16 v[60:63], v[132:135], v[164:167], v[60:63]
	v_mfma_f32_16x16x32_bf16 v[56:59], v[140:143], v[164:167], v[56:59]
	v_mfma_f32_16x16x32_bf16 v[44:47], v[132:135], v[172:175], v[44:47]
	v_mfma_f32_16x16x32_bf16 v[40:43], v[140:143], v[172:175], v[40:43]
	v_mfma_f32_16x16x32_bf16 v[28:31], v[132:135], v[210:213], v[28:31]
	v_mfma_f32_16x16x32_bf16 v[24:27], v[140:143], v[210:213], v[24:27]
	v_mfma_f32_16x16x32_bf16 v[12:15], v[132:135], v[218:221], v[12:15]
	v_mfma_f32_16x16x32_bf16 v[8:11], v[140:143], v[218:221], v[8:11]
	s_setprio 1
	s_setprio 0
	v_mfma_f32_16x16x32_bf16 v[52:55], v[144:147], v[160:163], v[52:55]
	v_mfma_f32_16x16x32_bf16 v[48:51], v[152:155], v[160:163], v[48:51]
	v_mfma_f32_16x16x32_bf16 v[36:39], v[144:147], v[168:171], v[36:39]
	v_mfma_f32_16x16x32_bf16 v[32:35], v[152:155], v[168:171], v[32:35]
	v_mfma_f32_16x16x32_bf16 v[20:23], v[144:147], v[176:179], v[20:23]
	v_mfma_f32_16x16x32_bf16 v[16:19], v[152:155], v[176:179], v[16:19]
	v_mfma_f32_16x16x32_bf16 v[4:7], v[144:147], v[214:217], v[4:7]
	v_mfma_f32_16x16x32_bf16 v[0:3], v[152:155], v[214:217], v[0:3]
	v_mfma_f32_16x16x32_bf16 v[52:55], v[148:151], v[164:167], v[52:55]
	v_mfma_f32_16x16x32_bf16 v[48:51], v[156:159], v[164:167], v[48:51]
	v_mfma_f32_16x16x32_bf16 v[36:39], v[148:151], v[172:175], v[36:39]
	v_mfma_f32_16x16x32_bf16 v[32:35], v[156:159], v[172:175], v[32:35]
	v_mfma_f32_16x16x32_bf16 v[20:23], v[148:151], v[210:213], v[20:23]
	v_mfma_f32_16x16x32_bf16 v[16:19], v[156:159], v[210:213], v[16:19]
	v_mfma_f32_16x16x32_bf16 v[4:7], v[148:151], v[218:221], v[4:7]
	v_mfma_f32_16x16x32_bf16 v[0:3], v[156:159], v[218:221], v[0:3]
	s_setprio 1
	s_barrier
	s_add_i32 s62, 0, 0x18000
	s_add_i32 s63, 0, 0x1c000
	v_add_u32_e32 v140, s62, v201
	v_add_u32_e32 v156, s63, v201
	ds_read_b128 v[120:123], v140
	ds_read_b128 v[132:135], v140 offset:1024
	ds_read_b128 v[136:139], v140 offset:2048
	ds_read_b128 v[140:143], v140 offset:3072
	ds_read_b128 v[144:147], v156
	ds_read_b128 v[148:151], v156 offset:1024
	ds_read_b128 v[152:155], v156 offset:2048
	ds_read_b128 v[156:159], v156 offset:3072
	s_add_u32 s40, s40, 0x40000
	s_addc_u32 s41, s41, 0
	s_mov_b32 m0, s47
	v_lshl_add_u64 v[230:231], s[40:41], 0, v[180:181]
	ds_read_b128 v[160:163], v209 offset:32768
	ds_read_b128 v[164:167], v209 offset:33792
	ds_read_b128 v[168:171], v209 offset:34816
	ds_read_b128 v[172:175], v209 offset:35840
	ds_read_b128 v[176:179], v209 offset:36864
	ds_read_b128 v[210:213], v209 offset:37888
	ds_read_b128 v[214:217], v209 offset:38912
	ds_read_b128 v[218:221], v209 offset:39936
	global_load_lds_dwordx4 v[230:231], off
	v_lshl_add_u64 v[230:231], s[40:41], 0, v[184:185]
	s_mov_b32 m0, s48
	s_nop 0
	global_load_lds_dwordx4 v[230:231], off
	s_waitcnt vmcnt(8)
	s_waitcnt lgkmcnt(0)
	s_barrier
	s_setprio 0
	s_waitcnt lgkmcnt(0)
	v_mfma_f32_16x16x32_bf16 v[128:131], v[120:123], v[160:163], v[128:131]
	v_mfma_f32_16x16x32_bf16 v[124:127], v[136:139], v[160:163], v[124:127]
	v_mfma_f32_16x16x32_bf16 v[108:111], v[120:123], v[168:171], v[108:111]
	v_mfma_f32_16x16x32_bf16 v[104:107], v[136:139], v[168:171], v[104:107]
	v_mfma_f32_16x16x32_bf16 v[92:95], v[120:123], v[176:179], v[92:95]
	v_mfma_f32_16x16x32_bf16 v[88:91], v[136:139], v[176:179], v[88:91]
	v_mfma_f32_16x16x32_bf16 v[76:79], v[120:123], v[214:217], v[76:79]
	v_mfma_f32_16x16x32_bf16 v[72:75], v[136:139], v[214:217], v[72:75]
	v_mfma_f32_16x16x32_bf16 v[128:131], v[132:135], v[164:167], v[128:131]
	v_mfma_f32_16x16x32_bf16 v[124:127], v[140:143], v[164:167], v[124:127]
	v_mfma_f32_16x16x32_bf16 v[108:111], v[132:135], v[172:175], v[108:111]
	v_mfma_f32_16x16x32_bf16 v[104:107], v[140:143], v[172:175], v[104:107]
	v_mfma_f32_16x16x32_bf16 v[92:95], v[132:135], v[210:213], v[92:95]
	v_mfma_f32_16x16x32_bf16 v[88:91], v[140:143], v[210:213], v[88:91]
	v_mfma_f32_16x16x32_bf16 v[76:79], v[132:135], v[218:221], v[76:79]
	v_mfma_f32_16x16x32_bf16 v[72:75], v[140:143], v[218:221], v[72:75]
	s_setprio 1
	s_setprio 0
	v_mfma_f32_16x16x32_bf16 v[116:119], v[144:147], v[160:163], v[116:119]
	v_mfma_f32_16x16x32_bf16 v[112:115], v[152:155], v[160:163], v[112:115]
	v_mfma_f32_16x16x32_bf16 v[100:103], v[144:147], v[168:171], v[100:103]
	v_mfma_f32_16x16x32_bf16 v[96:99], v[152:155], v[168:171], v[96:99]
	v_mfma_f32_16x16x32_bf16 v[84:87], v[144:147], v[176:179], v[84:87]
	v_mfma_f32_16x16x32_bf16 v[80:83], v[152:155], v[176:179], v[80:83]
	v_mfma_f32_16x16x32_bf16 v[68:71], v[144:147], v[214:217], v[68:71]
	v_mfma_f32_16x16x32_bf16 v[64:67], v[152:155], v[214:217], v[64:67]
	v_mfma_f32_16x16x32_bf16 v[116:119], v[148:151], v[164:167], v[116:119]
	v_mfma_f32_16x16x32_bf16 v[112:115], v[156:159], v[164:167], v[112:115]
	v_mfma_f32_16x16x32_bf16 v[100:103], v[148:151], v[172:175], v[100:103]
	v_mfma_f32_16x16x32_bf16 v[96:99], v[156:159], v[172:175], v[96:99]
	v_mfma_f32_16x16x32_bf16 v[84:87], v[148:151], v[210:213], v[84:87]
	v_mfma_f32_16x16x32_bf16 v[80:83], v[156:159], v[210:213], v[80:83]
	v_mfma_f32_16x16x32_bf16 v[68:71], v[148:151], v[218:221], v[68:71]
	v_mfma_f32_16x16x32_bf16 v[64:67], v[156:159], v[218:221], v[64:67]
	s_setprio 1
	s_barrier
	s_add_i32 s40, s62, s44
	v_lshl_add_u64 v[222:223], v[222:223], 0, s[12:13]
	s_mov_b32 m0, s40
	ds_read_b128 v[160:163], v209 offset:49152
	ds_read_b128 v[164:167], v209 offset:50176
	ds_read_b128 v[168:171], v209 offset:51200
	ds_read_b128 v[172:175], v209 offset:52224
	ds_read_b128 v[176:179], v209 offset:53248
	ds_read_b128 v[210:213], v209 offset:54272
	ds_read_b128 v[214:217], v209 offset:55296
	ds_read_b128 v[218:221], v209 offset:56320
	global_load_lds_dwordx4 v[222:223], off
	s_add_i32 m0, s40, 0x2000
	s_add_u32 s34, s34, 0x40080
	v_lshl_add_u64 v[222:223], v[224:225], 0, s[12:13]
	s_addc_u32 s35, s35, 0
	s_add_i32 s40, s63, s44
	global_load_lds_dwordx4 v[222:223], off
	v_lshl_add_u64 v[222:223], s[34:35], 0, v[182:183]
	s_mov_b32 m0, s40
	s_nop 0
	global_load_lds_dwordx4 v[222:223], off
	v_lshl_add_u64 v[222:223], s[34:35], 0, v[186:187]
	s_add_i32 m0, s40, 0x2000
	s_nop 0
	global_load_lds_dwordx4 v[222:223], off
	v_lshl_add_u64 v[222:223], v[226:227], 0, s[12:13]
	s_mov_b32 m0, s49
	s_nop 0
	global_load_lds_dwordx4 v[222:223], off
	v_lshl_add_u64 v[222:223], v[228:229], 0, s[12:13]
	s_mov_b32 m0, s50
	s_nop 0
	global_load_lds_dwordx4 v[222:223], off
	s_waitcnt vmcnt(8)
	s_waitcnt lgkmcnt(0)
	s_barrier
	s_setprio 0
	s_waitcnt lgkmcnt(0)
	v_mfma_f32_16x16x32_bf16 v[60:63], v[120:123], v[160:163], v[60:63]
	v_mfma_f32_16x16x32_bf16 v[56:59], v[136:139], v[160:163], v[56:59]
	v_mfma_f32_16x16x32_bf16 v[44:47], v[120:123], v[168:171], v[44:47]
	v_mfma_f32_16x16x32_bf16 v[40:43], v[136:139], v[168:171], v[40:43]
	v_mfma_f32_16x16x32_bf16 v[28:31], v[120:123], v[176:179], v[28:31]
	v_mfma_f32_16x16x32_bf16 v[24:27], v[136:139], v[176:179], v[24:27]
	v_mfma_f32_16x16x32_bf16 v[12:15], v[120:123], v[214:217], v[12:15]
	v_mfma_f32_16x16x32_bf16 v[8:11], v[136:139], v[214:217], v[8:11]
	v_mfma_f32_16x16x32_bf16 v[60:63], v[132:135], v[164:167], v[60:63]
	v_mfma_f32_16x16x32_bf16 v[56:59], v[140:143], v[164:167], v[56:59]
	v_mfma_f32_16x16x32_bf16 v[44:47], v[132:135], v[172:175], v[44:47]
	v_mfma_f32_16x16x32_bf16 v[40:43], v[140:143], v[172:175], v[40:43]
	v_mfma_f32_16x16x32_bf16 v[28:31], v[132:135], v[210:213], v[28:31]
	v_mfma_f32_16x16x32_bf16 v[24:27], v[140:143], v[210:213], v[24:27]
	v_mfma_f32_16x16x32_bf16 v[12:15], v[132:135], v[218:221], v[12:15]
	v_mfma_f32_16x16x32_bf16 v[8:11], v[140:143], v[218:221], v[8:11]
	s_setprio 1
	s_setprio 0
	v_mfma_f32_16x16x32_bf16 v[52:55], v[144:147], v[160:163], v[52:55]
	v_mfma_f32_16x16x32_bf16 v[48:51], v[152:155], v[160:163], v[48:51]
	v_mfma_f32_16x16x32_bf16 v[36:39], v[144:147], v[168:171], v[36:39]
	v_mfma_f32_16x16x32_bf16 v[32:35], v[152:155], v[168:171], v[32:35]
	v_mfma_f32_16x16x32_bf16 v[20:23], v[144:147], v[176:179], v[20:23]
	v_mfma_f32_16x16x32_bf16 v[16:19], v[152:155], v[176:179], v[16:19]
	v_mfma_f32_16x16x32_bf16 v[4:7], v[144:147], v[214:217], v[4:7]
	v_mfma_f32_16x16x32_bf16 v[0:3], v[152:155], v[214:217], v[0:3]
	v_mfma_f32_16x16x32_bf16 v[52:55], v[148:151], v[164:167], v[52:55]
	v_mfma_f32_16x16x32_bf16 v[48:51], v[156:159], v[164:167], v[48:51]
	v_mfma_f32_16x16x32_bf16 v[36:39], v[148:151], v[172:175], v[36:39]
	v_mfma_f32_16x16x32_bf16 v[32:35], v[156:159], v[172:175], v[32:35]
	v_mfma_f32_16x16x32_bf16 v[20:23], v[148:151], v[210:213], v[20:23]
	v_mfma_f32_16x16x32_bf16 v[16:19], v[156:159], v[210:213], v[16:19]
	v_mfma_f32_16x16x32_bf16 v[4:7], v[148:151], v[218:221], v[4:7]
	v_mfma_f32_16x16x32_bf16 v[0:3], v[156:159], v[218:221], v[0:3]
	s_setprio 1
	s_barrier
	s_add_i32 s61, s61, 2
	s_add_u32 s28, s28, 0x100
	s_addc_u32 s29, s29, 0
	s_add_u32 s59, s59, 0x100
	s_addc_u32 s60, s60, 0
	s_cmp_gt_u32 s61, 13
	s_cbranch_scc0 .LBB0_1200
	s_and_b64 vcc, exec, s[14:15]
	s_cbranch_vccz .LBB0_1203
	s_barrier

.LBB0_1206:
	s_setprio 0
	s_waitcnt vmcnt(0)
	s_barrier
